# mixer queue: next item's atomic pop issued right after the current item is known (result parked in a VGPR the mixer never touches)
# speedup vs baseline: 1.0015x; 1.0015x over previous
; #define LAS __attribute__((address_space(3)))
; __device__ __forceinline__ int opaque_tid(int wv) { int t = wv * 64 + (int)__builtin_amdgcn_mbcnt_hi(~0u, __builtin_amdgcn_mbcnt_lo(~0u, 0u)); asm volatile("" : "+v"(t)); return t; }
; __device__ __forceinline__ void mixer_phase(int wv, const Args& A, LAS unsigned char* lds) {
;     LAS int* itemw = (LAS int*)(lds + LDS_BYTES - 64);
;     unsigned* ctr = (unsigned*)(A.ws + WS_CTL);
;     constexpr int N_GP = 32, N_DP = 2048, N_DS = 32, N_GS = 128, NIT = N_GP + N_DP + N_DS + N_GS;
;     for (;;) {
;         __syncthreads();
;         if (opaque_tid(wv) == 0) *itemw = (int)atomicAdd(ctr, 1u);
;         __syncthreads();
;         int it = *itemw;
.LBB0_849:
	v_writelane_b32 v236, s86, 11
	s_or_b64 exec, exec, s[6:7]
	s_load_dwordx2 s[0:1], s[84:85], 0x28
	s_load_dwordx2 s[4:5], s[84:85], 0x48
	s_load_dwordx4 s[48:51], s[84:85], 0xd8
	s_waitcnt lgkmcnt(0)
	v_add_u32_e32 v0, 64, v178
	v_cmp_lt_i32_e32 vcc, v171, v0
	s_movk_i32 s96, 0x100
	v_writelane_b32 v236, s4, 12
	s_add_u32 s3, s48, 0x15020000
	v_cndmask_b32_e32 v1, v176, v171, vcc
	v_writelane_b32 v236, s5, 13
	v_writelane_b32 v236, s3, 14
	s_addc_u32 s3, s49, 0
	v_writelane_b32 v236, s3, 15
	v_writelane_b32 v236, s0, 16
	s_cmp_lg_u64 s[0:1], 0
	v_cmp_lt_i32_e32 vcc, v172, v0
	v_writelane_b32 v236, s1, 17
	s_cselect_b64 s[0:1], -1, 0
	s_add_u32 s3, s50, 0x324c1000
	v_writelane_b32 v236, s3, 18
	s_addc_u32 s3, s51, 0
	v_writelane_b32 v236, s3, 19
	s_add_u32 s3, s50, 0x34541000
	v_writelane_b32 v236, s3, 20
	s_addc_u32 s3, s51, 0
	s_add_u32 s76, s50, 0x365c1000
	s_addc_u32 s77, s51, 0
	v_writelane_b32 v236, s3, 21
	s_add_u32 s3, s50, 0x38641000
	v_writelane_b32 v236, s3, 22
	s_addc_u32 s3, s51, 0
	s_add_u32 s4, s50, 0x2a2c1000
	v_writelane_b32 v236, s3, 23
	s_addc_u32 s5, s51, 0
	v_writelane_b32 v236, s4, 24
	v_lshlrev_b32_e32 v171, 2, v1
	v_cndmask_b32_e32 v1, v176, v172, vcc
	v_writelane_b32 v236, s5, 25
	s_add_u32 s4, s50, 0x12d01000
	s_addc_u32 s5, s51, 0
	s_add_u32 s82, s50, 0x2081000
	v_writelane_b32 v236, s4, 26
	s_addc_u32 s83, s51, 0
	s_add_u32 s3, s50, 0x3d54d000
	v_writelane_b32 v236, s5, 27
	v_writelane_b32 v236, s3, 28
	s_addc_u32 s3, s51, 0
	s_add_u32 s84, s50, 0x2491000
	s_addc_u32 s85, s51, 0
	v_writelane_b32 v236, s3, 29
	s_add_u32 s3, s50, 0x3ea51000
	v_writelane_b32 v236, s3, 30
	s_addc_u32 s3, s51, 0
	s_add_u32 s86, s50, 0x2cb1000
	s_addc_u32 s87, s51, 0
	v_writelane_b32 v236, s3, 31
	s_add_u32 s3, s50, 0x3ec51000
	v_writelane_b32 v236, s3, 32
	s_addc_u32 s3, s51, 0
	v_cmp_lt_i32_e32 vcc, v173, v0
	v_writelane_b32 v236, s3, 33
	s_add_u32 s3, s48, 0x14c00000
	v_lshlrev_b32_e32 v172, 2, v1
	v_cndmask_b32_e32 v1, v176, v173, vcc
	v_cmp_lt_i32_e32 vcc, v174, v0
	v_writelane_b32 v236, s3, 34
	s_addc_u32 s3, s49, 0
	v_lshlrev_b32_e32 v173, 2, v1
	v_cndmask_b32_e32 v1, v176, v174, vcc
	v_cmp_lt_i32_e32 vcc, v175, v0
	v_writelane_b32 v236, s3, 35
	v_lshlrev_b32_e32 v174, 2, v1
	v_cndmask_b32_e32 v1, v176, v175, vcc
	v_cmp_lt_i32_e32 vcc, v177, v0
	v_writelane_b32 v236, s0, 36
	s_add_i32 s79, 0, 0x25fc0
	v_cndmask_b32_e32 v0, v176, v177, vcc
	v_writelane_b32 v236, s1, 37
	v_cndmask_b32_e64 v150, 0, 1, s[0:1]
	s_add_i32 s0, 0, 0x13000
	v_lshlrev_b32_e32 v175, 2, v1
	v_lshlrev_b32_e32 v176, 2, v0
	s_mov_b32 s49, 0
	v_mov_b32_e32 v1, 0
	v_mov_b32_e32 v151, 0xff800000
	s_movk_i32 s68, 0x400
	s_movk_i32 s71, 0x4c0
	s_movk_i32 s75, 0x2c0
	v_writelane_b32 v236, s0, 38
	v_mov_b32_e32 v152, 0x4c0
	s_movk_i32 s33, 0x5a
	s_mov_b32 s3, 0x3d800000
	s_mov_b32 s53, 0xff800000
	v_mov_b32_e32 v153, s79
	v_mov_b32_e32 v154, 0x3c845000
	v_mov_b32_e32 v155, 0x3c741000
	v_bfrev_b32_e32 v156, 1
	v_mov_b32_e32 v157, 0x2e00
	s_barrier
	v_writelane_b32 v236, s79, 39
	v_cmp_eq_u32_e32 vcc, 0, v170
	s_and_saveexec_b64 s[6:7], vcc
	v_mov_b32_e32 v237, 1
	s_nop 0
	global_atomic_add v237, v1, v237, s[50:51] sc0
	s_mov_b64 exec, s[6:7]
	s_branch .LBB0_853

; __device__ __forceinline__ int opaque_tid(int wv) { int t = wv * 64 + (int)__builtin_amdgcn_mbcnt_hi(~0u, __builtin_amdgcn_mbcnt_lo(~0u, 0u)); asm volatile("" : "+v"(t)); return t; }
; __device__ __forceinline__ void mixer_phase(int wv, const Args& A, LAS unsigned char* lds) {
;     ...
;     for (;;) {
;         __syncthreads();
;         if (opaque_tid(wv) == 0) *itemw = (int)atomicAdd(ctr, 1u);
;         __syncthreads();
;         int it = *itemw;
;         if (it >= NIT) break;
.LBB0_853:
	v_mov_b32_e32 v0, v170
	s_barrier
	s_nop 0
	v_cmp_eq_u32_e32 vcc, 0, v0
	s_and_saveexec_b64 s[6:7], vcc
	s_cbranch_execz .LBB0_857
	s_mov_b64 s[10:11], exec
	v_mbcnt_lo_u32_b32 v0, s10, 0
	v_mbcnt_hi_u32_b32 v0, s11, v0
	v_cmp_eq_u32_e32 vcc, 0, v0
	s_and_saveexec_b64 s[8:9], vcc
	s_cbranch_execz .LBB0_856
	s_waitcnt vmcnt(0)
	v_mov_b32_e32 v2, v237
	v_mov_b32_e32 v237, 1
	s_nop 0
	global_atomic_add v237, v1, v237, s[50:51] sc0
.LBB0_856:
	s_or_b64 exec, exec, s[8:9]
	v_readfirstlane_b32 s0, v2
	v_mov_b32_e32 v2, s79
	s_nop 0
	v_add_u32_e32 v0, s0, v0
	ds_write_b32 v2, v0
